# grid barrier flatten: XCD-mates poll TOPGEN directly, XGEN hop removed
# speedup vs baseline: 1.0058x; 1.0038x over previous
.LBB0_37:
	s_or_b64 exec, exec, s[10:11]
	v_cvt_f32_u32_e32 v4, v2
	s_waitcnt vmcnt(0)
	v_readfirstlane_b32 s8, v3
	s_add_u32 s6, s88, 0xfc03500
	s_addc_u32 s7, s89, 0
	v_rcp_iflag_f32_e32 v4, v4
	v_add_u32_e32 v5, s8, v0
	v_mul_f32_e32 v3, 0x4f7ffffe, v4
	v_cvt_u32_f32_e32 v3, v3
	v_sub_u32_e32 v4, 0, v2
	v_mul_lo_u32 v0, v4, v3
	v_mul_hi_u32 v0, v3, v0
	v_add_u32_e32 v0, v3, v0
	v_mul_hi_u32 v0, v5, v0
	v_mul_lo_u32 v3, v0, v2
	v_sub_u32_e32 v3, v5, v3
	v_add_u32_e32 v4, 1, v0
	v_sub_u32_e32 v6, v3, v2
	v_cmp_ge_u32_e32 vcc, v3, v2
	s_nop 1
	v_cndmask_b32_e32 v0, v0, v4, vcc
	v_cndmask_b32_e32 v3, v3, v6, vcc
	v_add_u32_e32 v4, 1, v0
	v_cmp_ge_u32_e32 vcc, v3, v2
	v_add_u32_e32 v3, 1, v5
	s_nop 0
	v_cndmask_b32_e32 v0, v0, v4, vcc
	v_mul_lo_u32 v4, v2, v0
	v_add_u32_e32 v2, v4, v2
	v_cmp_ne_u32_e32 vcc, v3, v2
	s_and_saveexec_b64 s[8:9], vcc
	s_xor_b64 s[8:9], exec, s[8:9]
	s_cbranch_execz .LBB0_51
	s_waitcnt lgkmcnt(0)
	v_mov_b32_e32 v1, 0
	global_load_dword v2, v1, s[6:7] sc1
	s_waitcnt vmcnt(0)
	v_cmp_eq_u32_e32 vcc, v2, v0
	s_and_saveexec_b64 s[10:11], vcc
	s_cbranch_execz .LBB0_50
	s_mov_b32 s22, 1
	s_mov_b64 s[12:13], 0
	s_branch .LBB0_41

.LBB0_68:
	s_or_b64 exec, exec, s[4:5]
	s_mov_b64 s[4:5], exec
	v_mbcnt_lo_u32_b32 v0, s4, 0
	v_mbcnt_hi_u32_b32 v0, s5, v0
	v_cmp_eq_u32_e32 vcc, 0, v0
	s_waitcnt vmcnt(0)
	buffer_inv sc1
	s_and_saveexec_b64 s[8:9], vcc
	s_cbranch_execz .LBB0_70
	s_bcnt1_i32_b64 s4, s[4:5]
	v_mov_b32_e32 v0, 0
	v_mov_b32_e32 v1, s4
	s_nop 0

.LBB0_152:
	s_or_b64 exec, exec, s[12:13]
	v_cvt_f32_u32_e32 v4, v2
	s_waitcnt vmcnt(0)
	v_readfirstlane_b32 s10, v3
	s_add_u32 s8, s88, 0xfc03500
	s_addc_u32 s9, s89, 0
	v_rcp_iflag_f32_e32 v4, v4
	v_add_u32_e32 v5, s10, v0
	v_mul_f32_e32 v3, 0x4f7ffffe, v4
	v_cvt_u32_f32_e32 v3, v3
	v_sub_u32_e32 v4, 0, v2
	v_mul_lo_u32 v0, v4, v3
	v_mul_hi_u32 v0, v3, v0
	v_add_u32_e32 v0, v3, v0
	v_mul_hi_u32 v0, v5, v0
	v_mul_lo_u32 v3, v0, v2
	v_sub_u32_e32 v3, v5, v3
	v_add_u32_e32 v4, 1, v0
	v_cmp_ge_u32_e32 vcc, v3, v2
	s_nop 1
	v_cndmask_b32_e32 v0, v0, v4, vcc
	v_sub_u32_e32 v4, v3, v2
	v_cndmask_b32_e32 v3, v3, v4, vcc
	v_add_u32_e32 v4, 1, v0
	v_cmp_ge_u32_e32 vcc, v3, v2
	v_add_u32_e32 v3, 1, v5
	s_nop 0
	v_cndmask_b32_e32 v0, v0, v4, vcc
	v_mul_lo_u32 v4, v2, v0
	v_add_u32_e32 v2, v4, v2
	v_cmp_ne_u32_e32 vcc, v3, v2
	s_and_saveexec_b64 s[10:11], vcc
	s_xor_b64 s[10:11], exec, s[10:11]
	s_cbranch_execz .LBB0_166
	s_waitcnt lgkmcnt(0)
	v_mov_b32_e32 v1, 0
	global_load_dword v2, v1, s[8:9] sc1
	s_waitcnt vmcnt(0)
	v_cmp_eq_u32_e32 vcc, v2, v0
	s_and_saveexec_b64 s[12:13], vcc
	s_cbranch_execz .LBB0_165
	s_mov_b32 s24, 1
	s_mov_b64 s[14:15], 0
	s_branch .LBB0_156

.LBB0_183:
	s_or_b64 exec, exec, s[6:7]
	s_mov_b64 s[6:7], exec
	v_mbcnt_lo_u32_b32 v0, s6, 0
	v_mbcnt_hi_u32_b32 v0, s7, v0
	v_cmp_eq_u32_e32 vcc, 0, v0
	s_waitcnt vmcnt(0)
	buffer_inv sc1
	s_and_saveexec_b64 s[10:11], vcc
	s_cbranch_execz .LBB0_185
	s_bcnt1_i32_b64 s6, s[6:7]
	v_mov_b32_e32 v0, 0
	v_mov_b32_e32 v1, s6
	s_nop 0

.LBB0_215:
	s_or_b64 exec, exec, s[12:13]
	v_cvt_f32_u32_e32 v4, v2
	s_waitcnt vmcnt(0)
	v_readfirstlane_b32 s8, v3
	s_add_u32 s6, s88, 0xfc03500
	s_addc_u32 s7, s89, 0
	v_rcp_iflag_f32_e32 v4, v4
	v_add_u32_e32 v5, s8, v0
	v_mul_f32_e32 v3, 0x4f7ffffe, v4
	v_cvt_u32_f32_e32 v3, v3
	v_sub_u32_e32 v4, 0, v2
	v_mul_lo_u32 v0, v4, v3
	v_mul_hi_u32 v0, v3, v0
	v_add_u32_e32 v0, v3, v0
	v_mul_hi_u32 v0, v5, v0
	v_mul_lo_u32 v3, v0, v2
	v_sub_u32_e32 v3, v5, v3
	v_add_u32_e32 v4, 1, v0
	v_cmp_ge_u32_e32 vcc, v3, v2
	s_nop 1
	v_cndmask_b32_e32 v0, v0, v4, vcc
	v_sub_u32_e32 v4, v3, v2
	v_cndmask_b32_e32 v3, v3, v4, vcc
	v_add_u32_e32 v4, 1, v0
	v_cmp_ge_u32_e32 vcc, v3, v2
	v_add_u32_e32 v3, 1, v5
	s_nop 0
	v_cndmask_b32_e32 v0, v0, v4, vcc
	v_mul_lo_u32 v4, v2, v0
	v_add_u32_e32 v2, v4, v2
	v_cmp_ne_u32_e32 vcc, v3, v2
	s_and_saveexec_b64 s[8:9], vcc
	s_xor_b64 s[8:9], exec, s[8:9]
	s_cbranch_execz .LBB0_229
	s_waitcnt lgkmcnt(0)
	v_mov_b32_e32 v1, 0
	global_load_dword v2, v1, s[6:7] sc1
	s_waitcnt vmcnt(0)
	v_cmp_eq_u32_e32 vcc, v2, v0
	s_and_saveexec_b64 s[12:13], vcc
	s_cbranch_execz .LBB0_228
	s_mov_b32 s24, 1
	s_mov_b64 s[14:15], 0
	s_branch .LBB0_219

.LBB0_368:
	s_or_b64 exec, exec, s[6:7]
	v_cvt_f32_u32_e32 v4, v2
	s_waitcnt vmcnt(0)
	v_readfirstlane_b32 s4, v3
	s_add_u32 s2, s88, 0xfc03500
	s_addc_u32 s3, s89, 0
	v_rcp_iflag_f32_e32 v4, v4
	v_add_u32_e32 v5, s4, v1
	v_mul_f32_e32 v3, 0x4f7ffffe, v4
	v_cvt_u32_f32_e32 v3, v3
	v_sub_u32_e32 v4, 0, v2
	v_mul_lo_u32 v1, v4, v3
	v_mul_hi_u32 v1, v3, v1
	v_add_u32_e32 v1, v3, v1
	v_mul_hi_u32 v1, v5, v1
	v_mul_lo_u32 v3, v1, v2
	v_sub_u32_e32 v3, v5, v3
	v_add_u32_e32 v4, 1, v1
	v_cmp_ge_u32_e32 vcc, v3, v2
	s_nop 1
	v_cndmask_b32_e32 v1, v1, v4, vcc
	v_sub_u32_e32 v4, v3, v2
	v_cndmask_b32_e32 v3, v3, v4, vcc
	v_add_u32_e32 v4, 1, v1
	v_cmp_ge_u32_e32 vcc, v3, v2
	v_add_u32_e32 v3, 1, v5
	s_nop 0
	v_cndmask_b32_e32 v1, v1, v4, vcc
	v_mul_lo_u32 v4, v2, v1
	v_add_u32_e32 v2, v4, v2
	v_cmp_ne_u32_e32 vcc, v3, v2
	s_and_saveexec_b64 s[4:5], vcc
	s_xor_b64 s[4:5], exec, s[4:5]
	s_cbranch_execz .LBB0_382
	s_waitcnt lgkmcnt(0)
	v_mov_b32_e32 v0, 0
	global_load_dword v2, v0, s[2:3] sc1
	s_waitcnt vmcnt(0)
	v_cmp_eq_u32_e32 vcc, v2, v1
	s_and_saveexec_b64 s[6:7], vcc
	s_cbranch_execz .LBB0_381
	s_mov_b32 s20, 1
	s_mov_b64 s[10:11], 0
	s_branch .LBB0_372

.LBB0_399:
	s_or_b64 exec, exec, s[4:5]
	s_mov_b64 s[4:5], exec
	v_mbcnt_lo_u32_b32 v0, s4, 0
	v_mbcnt_hi_u32_b32 v0, s5, v0
	v_cmp_eq_u32_e32 vcc, 0, v0
	s_waitcnt vmcnt(0)
	buffer_inv sc1
	s_and_saveexec_b64 s[6:7], vcc
	s_cbranch_execz .LBB0_401
	s_bcnt1_i32_b64 s4, s[4:5]
	v_mov_b32_e32 v0, 0
	v_mov_b32_e32 v1, s4
	s_nop 0

.LBB0_718:
	s_or_b64 exec, exec, s[10:11]
	v_cvt_f32_u32_e32 v4, v2
	s_waitcnt vmcnt(0)
	v_readfirstlane_b32 s8, v3
	s_add_u32 s6, s88, 0xfc03500
	s_addc_u32 s7, s89, 0
	v_rcp_iflag_f32_e32 v4, v4
	v_add_u32_e32 v5, s8, v0
	v_mul_f32_e32 v3, 0x4f7ffffe, v4
	v_cvt_u32_f32_e32 v3, v3
	v_sub_u32_e32 v4, 0, v2
	v_mul_lo_u32 v0, v4, v3
	v_mul_hi_u32 v0, v3, v0
	v_add_u32_e32 v0, v3, v0
	v_mul_hi_u32 v0, v5, v0
	v_mul_lo_u32 v3, v0, v2
	v_sub_u32_e32 v3, v5, v3
	v_add_u32_e32 v4, 1, v0
	v_cmp_ge_u32_e32 vcc, v3, v2
	s_nop 1
	v_cndmask_b32_e32 v0, v0, v4, vcc
	v_sub_u32_e32 v4, v3, v2
	v_cndmask_b32_e32 v3, v3, v4, vcc
	v_add_u32_e32 v4, 1, v0
	v_cmp_ge_u32_e32 vcc, v3, v2
	v_add_u32_e32 v3, 1, v5
	s_nop 0
	v_cndmask_b32_e32 v0, v0, v4, vcc
	v_mul_lo_u32 v4, v2, v0
	v_add_u32_e32 v2, v4, v2
	v_cmp_ne_u32_e32 vcc, v3, v2
	s_and_saveexec_b64 s[8:9], vcc
	s_xor_b64 s[8:9], exec, s[8:9]
	s_cbranch_execz .LBB0_732
	s_waitcnt lgkmcnt(0)
	v_mov_b32_e32 v1, 0
	global_load_dword v2, v1, s[6:7] sc1
	s_waitcnt vmcnt(0)
	v_cmp_eq_u32_e32 vcc, v2, v0
	s_and_saveexec_b64 s[10:11], vcc
	s_cbranch_execz .LBB0_731
	s_mov_b32 s22, 1
	s_mov_b64 s[12:13], 0
	s_branch .LBB0_722

.LBB0_1200:
	s_or_b64 exec, exec, s[8:9]
	v_cvt_f32_u32_e32 v4, v2
	s_waitcnt vmcnt(0)
	v_readfirstlane_b32 s6, v3
	s_add_u32 s4, s88, 0xfc03500
	s_addc_u32 s5, s89, 0
	v_rcp_iflag_f32_e32 v4, v4
	v_add_u32_e32 v5, s6, v0
	v_mul_f32_e32 v3, 0x4f7ffffe, v4
	v_cvt_u32_f32_e32 v3, v3
	v_sub_u32_e32 v4, 0, v2
	v_mul_lo_u32 v0, v4, v3
	v_mul_hi_u32 v0, v3, v0
	v_add_u32_e32 v0, v3, v0
	v_mul_hi_u32 v0, v5, v0
	v_mul_lo_u32 v3, v0, v2
	v_sub_u32_e32 v3, v5, v3
	v_add_u32_e32 v4, 1, v0
	v_cmp_ge_u32_e32 vcc, v3, v2
	s_nop 1
	v_cndmask_b32_e32 v0, v0, v4, vcc
	v_sub_u32_e32 v4, v3, v2
	v_cndmask_b32_e32 v3, v3, v4, vcc
	v_add_u32_e32 v4, 1, v0
	v_cmp_ge_u32_e32 vcc, v3, v2
	v_add_u32_e32 v3, 1, v5
	s_nop 0
	v_cndmask_b32_e32 v0, v0, v4, vcc
	v_mul_lo_u32 v4, v2, v0
	v_add_u32_e32 v2, v4, v2
	v_cmp_ne_u32_e32 vcc, v3, v2
	s_and_saveexec_b64 s[6:7], vcc
	s_xor_b64 s[6:7], exec, s[6:7]
	s_cbranch_execz .LBB0_1214
	s_waitcnt lgkmcnt(0)
	v_mov_b32_e32 v1, 0
	global_load_dword v2, v1, s[4:5] sc1
	s_waitcnt vmcnt(0)
	v_cmp_eq_u32_e32 vcc, v2, v0
	s_and_saveexec_b64 s[8:9], vcc
	s_cbranch_execz .LBB0_1213
	s_mov_b32 s20, 1
	s_mov_b64 s[10:11], 0
	s_branch .LBB0_1204

.LBB0_1231:
	s_or_b64 exec, exec, s[2:3]
	s_mov_b64 s[2:3], exec
	v_mbcnt_lo_u32_b32 v0, s2, 0
	v_mbcnt_hi_u32_b32 v0, s3, v0
	v_cmp_eq_u32_e32 vcc, 0, v0
	s_waitcnt vmcnt(0)
	buffer_inv sc1
	s_and_saveexec_b64 s[6:7], vcc
	s_cbranch_execz .LBB0_1233
	s_bcnt1_i32_b64 s2, s[2:3]
	v_mov_b32_e32 v0, 0
	v_mov_b32_e32 v1, s2
	s_nop 0

.LBB0_1574:
	s_cmp_lt_i32 s90, 13
	s_cselect_b64 s[20:21], -1, 0
	s_cmp_gt_i32 s91, 12
	s_cselect_b64 s[0:1], -1, 0
	s_and_b64 s[0:1], s[20:21], s[0:1]
	s_andn2_b64 vcc, exec, s[0:1]
	s_cbranch_vccnz .LBB0_1712
	s_mov_b64 s[0:1], s[92:93]
	s_mul_i32 s18, s1, s0
	s_add_u32 s0, s88, 0xfc00200
	s_addc_u32 s1, s89, 0
	s_add_u32 s38, s88, 0xfc00400
	v_writelane_b32 v254, s0, 27
	s_addc_u32 s39, s89, 0
	s_nop 0
	v_writelane_b32 v254, s1, 28
	s_add_u32 s0, s88, 0xfc00500
	s_addc_u32 s1, s89, 0
	v_writelane_b32 v253, s0, 7
	s_nop 1
	v_writelane_b32 v253, s1, 8
	s_add_u32 s0, s88, 0xfc00600
	s_addc_u32 s1, s89, 0
	s_add_u32 s60, s88, 0xfc00700
	s_addc_u32 s61, s89, 0
	s_add_u32 s62, s88, 0xfc00800
	s_addc_u32 s63, s89, 0
	s_add_u32 s64, s88, 0xfc00900
	s_addc_u32 s65, s89, 0
	s_add_u32 s66, s88, 0xfc00a00
	s_addc_u32 s67, s89, 0
	s_add_u32 s68, s88, 0xfc00b00
	s_addc_u32 s69, s89, 0
	s_add_u32 s72, s88, 0xfc00c00
	s_addc_u32 s73, s89, 0
	s_add_u32 s74, s88, 0xfc00d00
	s_addc_u32 s75, s89, 0
	s_add_u32 s76, s88, 0xfc00e00
	s_addc_u32 s77, s89, 0
	s_add_u32 s78, s88, 0xfc00f00
	s_addc_u32 s79, s89, 0
	s_add_u32 s80, s88, 0xfc01000
	s_addc_u32 s81, s89, 0
	s_add_u32 s82, s88, 0xfc01100
	s_addc_u32 s83, s89, 0
	s_add_u32 s84, s88, 0xfc01200
	s_addc_u32 s85, s89, 0
	v_writelane_b32 v254, s0, 9
	s_add_u32 s86, s88, 0xfc01300
	s_addc_u32 s87, s89, 0
	v_writelane_b32 v254, s1, 10
	v_readlane_b32 s0, v253, 5
	s_cmp_eq_u32 s0, 15
	s_cselect_b64 s[26:27], -1, 0
	s_cmp_eq_u32 s0, 14
	s_cselect_b64 s[28:29], -1, 0
	s_cmp_eq_u32 s0, 13
	s_cselect_b64 s[30:31], -1, 0
	s_cmp_eq_u32 s0, 12
	s_cselect_b64 s[34:35], -1, 0
	s_cmp_eq_u32 s0, 11
	s_cselect_b64 s[42:43], -1, 0
	s_cmp_eq_u32 s0, 10
	s_cselect_b64 s[2:3], -1, 0
	v_writelane_b32 v254, s2, 7
	s_cmp_eq_u32 s0, 9
	s_nop 0
	v_writelane_b32 v254, s3, 8
	s_cselect_b64 s[2:3], -1, 0
	v_writelane_b32 v254, s2, 31
	s_cmp_eq_u32 s0, 8
	s_nop 0
	v_writelane_b32 v254, s3, 32
	s_cselect_b64 s[2:3], -1, 0
	v_writelane_b32 v254, s2, 33
	s_cmp_eq_u32 s0, 7
	s_nop 0
	v_writelane_b32 v254, s3, 34
	s_cselect_b64 s[2:3], -1, 0
	v_writelane_b32 v254, s2, 35
	s_cmp_eq_u32 s0, 6
	s_nop 0
	v_writelane_b32 v254, s3, 36
	s_cselect_b64 s[2:3], -1, 0
	v_writelane_b32 v254, s2, 37
	s_cmp_eq_u32 s0, 5
	s_nop 0
	v_writelane_b32 v254, s3, 38
	s_cselect_b64 s[2:3], -1, 0
	v_writelane_b32 v254, s2, 39
	s_cmp_eq_u32 s0, 4
	s_nop 0
	v_writelane_b32 v254, s3, 40
	s_cselect_b64 s[2:3], -1, 0
	v_writelane_b32 v254, s2, 41
	s_cmp_eq_u32 s0, 3
	s_nop 0
	v_writelane_b32 v254, s3, 42
	s_cselect_b64 s[2:3], -1, 0
	v_writelane_b32 v254, s2, 43
	s_cmp_eq_u32 s0, 2
	s_nop 0
	v_writelane_b32 v254, s3, 44
	s_cselect_b64 s[2:3], -1, 0
	v_writelane_b32 v254, s2, 45
	s_cmp_eq_u32 s0, 1
	s_nop 0
	v_writelane_b32 v254, s3, 46
	s_cselect_b64 s[2:3], -1, 0
	v_writelane_b32 v254, s2, 47
	s_cmp_eq_u32 s0, 0
	s_nop 0
	v_writelane_b32 v254, s3, 48
	s_cselect_b64 s[2:3], -1, 0
	v_writelane_b32 v254, s2, 49
	s_lshl_b32 s0, s0, 8
	s_nop 0
	v_writelane_b32 v254, s3, 50
	v_readlane_b32 s2, v253, 3
	v_readlane_b32 s3, v253, 4
	s_add_u32 s0, s2, s0
	s_addc_u32 s1, s3, 0
	s_add_u32 s10, s0, 0x1400
	s_addc_u32 s11, s1, 0
	s_add_u32 s0, s88, 0xfc03500
	s_addc_u32 s1, s89, 0
	s_add_u32 s22, s88, 0xfc03400
	v_writelane_b32 v254, s0, 29
	s_addc_u32 s23, s89, 0
	s_nop 0
	v_writelane_b32 v254, s1, 30
	s_add_u32 s0, s88, 0xfc03500
	s_addc_u32 s1, s89, 0
	v_writelane_b32 v254, s0, 25
	s_andn2_b64 vcc, exec, s[36:37]
	s_nop 0
	v_writelane_b32 v254, s1, 26
	v_readlane_b32 s0, v253, 2
	s_mul_i32 s18, s18, s0
	s_cbranch_vccnz .LBB0_1629
	s_waitcnt vmcnt(0)
	s_waitcnt lgkmcnt(0)
	s_barrier
	s_mov_b64 s[0:1], exec
	v_readlane_b32 s2, v253, 0
	v_readlane_b32 s3, v253, 1
	s_and_b64 s[2:3], s[0:1], s[2:3]
	s_mov_b64 exec, s[2:3]
	s_cbranch_execz .LBB0_1628
	v_mov_b32_e32 v16, 0
	s_waitcnt vmcnt(0) expcnt(0) lgkmcnt(0)
	ds_read_b32 v2, v16
	ds_read_b32 v0, v16 offset:4
	s_waitcnt lgkmcnt(1)
	v_cmp_ne_u32_e32 vcc, 0, v2
	s_cbranch_vccnz .LBB0_1592
	s_mov_b32 s8, 1
	s_branch .LBB0_1580

.LBB0_1625:
	s_or_b64 exec, exec, s[2:3]
	s_mov_b64 s[2:3], exec
	v_mbcnt_lo_u32_b32 v0, s2, 0
	v_mbcnt_hi_u32_b32 v0, s3, v0
	v_cmp_eq_u32_e32 vcc, 0, v0
	s_waitcnt vmcnt(0)
	buffer_inv sc1
	s_and_saveexec_b64 s[4:5], vcc
	s_cbranch_execz .LBB0_1627
	s_bcnt1_i32_b64 s2, s[2:3]
	v_mov_b32_e32 v1, s2
	v_readlane_b32 s2, v254, 29
	v_mov_b32_e32 v0, 0
	v_readlane_b32 s3, v254, 30
	s_nop 4
	s_nop 0
